# first barrier: per-XCD arrival-count post issued by thread 0 after the workgroup barrier, so wave 0 no longer waits for that atomic's acknowledgement before the barrier
# baseline (speedup 1.0000x reference)
; #define LAS __attribute__((address_space(3)))
; __device__ __forceinline__ unsigned xb_add(unsigned* p, unsigned v) { return __hip_atomic_fetch_add(p, v, __ATOMIC_RELAXED, __HIP_MEMORY_SCOPE_AGENT); }
; __device__ __forceinline__ unsigned xb_xcc_id() { return (unsigned)__builtin_amdgcn_s_getreg((3 << 11) | 20) & 0xFu; }
; __device__ __forceinline__ XcdBarrier xcd_barrier_post(unsigned* bar, volatile LAS unsigned* st) {
;     XcdBarrier b; b.bar = bar; b.x = xb_xcc_id(); b.st = st;
;     if (threadIdx.x == 0) (void)xb_add(&bar[XB_XCNT(b.x)], 1u);
;     return b;
; }
; __device__ __forceinline__ void xcd_barrier(const XcdBarrier& b) {
;     asm volatile("s_waitcnt vmcnt(0)" ::: "memory");
;     __syncthreads();
;     if (threadIdx.x == 0) {
;         unsigned* bar = b.bar;
;         __builtin_amdgcn_s_waitcnt(0);
;         unsigned nloc = b.st[0], nx = b.st[1];
;         if (nloc == 0u) { xcd_barrier_complete(bar, b.x, nloc, nx); b.st[0] = nloc; b.st[1] = nx; }
;         const unsigned old = xb_add(&bar[XB_XSUB(b.x)], 1u);
.Linit_acq:
.Linit_post:
.Linit_done:
	s_or_b64 exec, exec, s[4:5]
	s_waitcnt vmcnt(0)
	s_waitcnt lgkmcnt(0)
	s_barrier
	v_readfirstlane_b32 s2, v152
	s_cmp_lg_u32 s2, 64
	s_cbranch_scc1 .Leinv_skip_0
	buffer_inv sc1
	s_waitcnt vmcnt(0)
.Leinv_skip_0:
	s_mov_b64 s[0:1], exec
	v_readlane_b32 s2, v255, 2
	v_readlane_b32 s3, v255, 3
	s_and_b64 s[2:3], s[0:1], s[2:3]
	s_mov_b64 exec, s[2:3]
	s_cbranch_execz .LBB0_115
	s_add_i32 s2, 0, 0x20000
	v_mov_b32_e32 v0, s2
	s_waitcnt vmcnt(0) expcnt(0) lgkmcnt(0)
	ds_read_b32 v2, v0
	s_add_i32 s2, 0, 0x20004
	v_mov_b32_e32 v0, s2
	ds_read_b32 v0, v0
	s_waitcnt lgkmcnt(1)
	v_cmp_ne_u32_e32 vcc, 0, v2
	s_cbranch_vccnz .LBB0_79
	v_readlane_b32 s2, v255, 1
	s_nop 3
	s_lshl_b32 s2, s2, 8
	v_mov_b32_e32 v3, s2
	v_mov_b32_e32 v4, 1
	global_atomic_add v3, v4, s[96:97] offset:1024
	s_add_u32 s4, s72, 0x580200
	s_addc_u32 s5, s73, 0
	s_add_u32 s6, s72, 0x580400
	s_addc_u32 s7, s73, 0
	s_add_u32 s8, s72, 0x580500
	s_addc_u32 s9, s73, 0
	s_add_u32 s10, s72, 0x580600
	s_addc_u32 s11, s73, 0
	s_add_u32 s12, s72, 0x580700
	s_addc_u32 s13, s73, 0
	s_add_u32 s14, s72, 0x580800
	s_addc_u32 s15, s73, 0
	s_add_u32 s28, s72, 0x580900
	s_addc_u32 s29, s73, 0
	s_add_u32 s30, s72, 0x580a00
	s_addc_u32 s31, s73, 0
	s_add_u32 s34, s72, 0x580b00
	s_addc_u32 s35, s73, 0
	s_add_u32 s36, s72, 0x580c00
	s_addc_u32 s37, s73, 0
	s_add_u32 s38, s72, 0x580d00
	s_addc_u32 s39, s73, 0
	s_add_u32 s40, s72, 0x580e00
	s_addc_u32 s41, s73, 0
	s_add_u32 s42, s72, 0x580f00
	s_addc_u32 s43, s73, 0
	s_add_u32 s44, s72, 0x581000
	s_addc_u32 s45, s73, 0
	s_add_u32 s46, s72, 0x581100
	s_addc_u32 s47, s73, 0
	s_add_u32 s76, s72, 0x581200
	v_readlane_b32 s2, v255, 0
	s_addc_u32 s77, s73, 0
	s_mul_i32 s2, s75, s2
	s_add_u32 s78, s72, 0x581300
	s_mul_i32 s2, s2, s74
	s_addc_u32 s79, s73, 0
	s_mov_b32 s3, 1
	v_mov_b32_e32 v16, 0
	s_branch .LBB0_66
